# G1 non-aligned epilogue: pre-epilogue barrier only on last unit, post-epilogue barrier removed
# baseline (speedup 1.0000x reference)
.LBB0_268:
	s_andn2_b64 vcc, s[16:17], s[36:37]
	s_cbranch_vccz .LBB0_270
	s_barrier

.LBB0_273:
	s_andn2_b64 vcc, exec, s[8:9]
	s_cbranch_vccnz .LBB0_243
	s_nop 0
	s_branch .LBB0_243
